# phase 2 (P tiles): L2 warm-up of this and the next tile's Q/K chunk ahead of the first loads
# baseline (speedup 1.0000x reference)
.LBB0_330:
	v_mov_b32_e32 v40, v220
	s_add_u32 s0, s72, s4
	v_ashrrev_i32_e32 v24, 2, v40
	v_min_i32_e32 v0, 0x7f, v24
	v_lshlrev_b32_e32 v1, 4, v40
	v_and_b32_e32 v6, 48, v1
	v_ashrrev_i32_e32 v1, 31, v0
	v_add_u32_e32 v26, 64, v24
	v_lshlrev_b64 v[0:1], 9, v[0:1]
	v_ashrrev_i32_e32 v25, 31, v24
	v_min_i32_e32 v2, 0x7f, v26
	s_addc_u32 s1, s73, s5
	v_lshlrev_b32_e32 v153, 7, v220
	v_mov_b32_e32 v151, s1
	v_add_co_u32_e32 v150, vcc, s0, v153
	v_addc_co_u32_e32 v151, vcc, 0, v151, vcc
	v_add_co_u32_e32 v154, vcc, s3, v150
	v_addc_co_u32_e32 v155, vcc, 0, v151, vcc
	global_load_dword v152, v[154:155], off
	v_add_co_u32_e32 v154, vcc, 0x8000, v154
	v_addc_co_u32_e32 v155, vcc, 0, v155, vcc
	global_load_dword v152, v[154:155], off
	v_add_co_u32_e32 v154, vcc, s22, v150
	v_addc_co_u32_e32 v155, vcc, 0, v151, vcc
	global_load_dword v152, v[154:155], off
	v_add_co_u32_e32 v154, vcc, 0x8000, v154
	v_addc_co_u32_e32 v155, vcc, 0, v155, vcc
	global_load_dword v152, v[154:155], off
	v_mov_b32_e32 v153, s9
	v_add_co_u32_e32 v150, vcc, s8, v150
	v_addc_co_u32_e32 v151, vcc, v151, v153, vcc
	v_add_co_u32_e32 v154, vcc, s3, v150
	v_addc_co_u32_e32 v155, vcc, 0, v151, vcc
	global_load_dword v152, v[154:155], off
	v_add_co_u32_e32 v154, vcc, 0x8000, v154
	v_addc_co_u32_e32 v155, vcc, 0, v155, vcc
	global_load_dword v152, v[154:155], off
	v_add_co_u32_e32 v154, vcc, s22, v150
	v_addc_co_u32_e32 v155, vcc, 0, v151, vcc
	global_load_dword v152, v[154:155], off
	v_add_co_u32_e32 v154, vcc, 0x8000, v154
	v_addc_co_u32_e32 v155, vcc, 0, v155, vcc
	global_load_dword v152, v[154:155], off
	v_lshrrev_b32_e32 v0, 4, v24
	v_lshlrev_b32_e32 v0, 13, v0
	v_lshl_or_b32 v0, v6, 4, v0
	v_and_b32_e32 v253, 15, v24
	v_lshl_or_b32 v0, v253, 4, v0
	v_add_u32_e32 v0, 0x1000, v0
	v_mov_b32_e32 v1, 0
	v_lshlrev_b64 v[4:5], 9, v[24:25]
	v_lshl_add_u64 v[0:1], s[0:1], 0, v[0:1]
	v_ashrrev_i32_e32 v3, 31, v2
	v_or_b32_e32 v4, v4, v6
	v_add_co_u32_e32 v0, vcc, s3, v0
	v_lshlrev_b64 v[2:3], 9, v[2:3]
	v_lshl_add_u64 v[4:5], s[0:1], 0, v[4:5]
	v_addc_co_u32_e32 v1, vcc, 0, v1, vcc
	v_lshrrev_b32_e32 v2, 4, v24
	v_lshlrev_b32_e32 v2, 13, v2
	v_lshl_or_b32 v2, v6, 4, v2
	v_and_b32_e32 v253, 15, v24
	v_lshl_or_b32 v2, v253, 4, v2
	v_add_u32_e32 v2, 0x9000, v2
	v_mov_b32_e32 v3, 0
	v_lshl_add_u64 v[6:7], s[0:1], 0, v[2:3]
	v_add_co_u32_e32 v2, vcc, s22, v4
	global_load_dwordx4 v[8:11], v[0:1], off offset:-4096
	s_nop 0
	v_addc_co_u32_e32 v3, vcc, 0, v5, vcc
	v_add_co_u32_e32 v4, vcc, s23, v4
	global_load_dwordx4 v[12:15], v[2:3], off
	s_nop 0
	v_addc_co_u32_e32 v5, vcc, 0, v5, vcc
	v_add_co_u32_e32 v6, vcc, s3, v6
	global_load_dwordx4 v[16:19], v[4:5], off
	s_nop 0
	v_addc_co_u32_e32 v7, vcc, 0, v7, vcc
	global_load_dwordx4 v[20:23], v[6:7], off offset:-4096
	v_lshrrev_b32_e32 v41, 4, v40
	v_sub_u32_e32 v25, 0, v41
	v_xor_b32_e32 v25, v40, v25
	v_lshlrev_b32_e32 v25, 4, v25
	v_and_b32_e32 v25, 48, v25
	v_lshl_or_b32 v148, v24, 6, v25
	v_lshl_or_b32 v149, v26, 6, v25
	global_load_dwordx4 v[24:27], v[2:3], off offset:64
	global_load_dwordx4 v[28:31], v[4:5], off offset:64
	global_load_dwordx4 v[32:35], v[0:1], off offset:-3072
	global_load_dwordx4 v[36:39], v[6:7], off offset:-3072
	v_lshrrev_b32_e32 v42, 2, v40
	v_sub_u32_e32 v42, 0, v42
	v_xor_b32_e32 v41, v41, v42
	v_and_b32_e32 v42, 15, v40
	v_lshrrev_b32_e32 v43, 1, v40
	v_lshlrev_b32_e32 v41, 4, v41
	v_and_or_b32 v42, v43, s24, v42
	v_and_b32_e32 v41, 48, v41
	v_lshlrev_b32_e32 v40, 6, v40
	v_lshl_or_b32 v140, v42, 6, v41
	v_and_or_b32 v144, v40, s25, v41
	s_waitcnt vmcnt(7)
	ds_write_b128 v148, v[8:11]
	s_waitcnt vmcnt(6)
	ds_write_b128 v148, v[12:15] offset:16384
	s_waitcnt vmcnt(5)
	ds_write_b128 v149, v[16:19] offset:16384
	s_waitcnt vmcnt(4)
	ds_write_b128 v149, v[20:23]
	s_waitcnt lgkmcnt(0)
	s_barrier
	global_load_dwordx4 v[8:11], v[0:1], off offset:-2048
	global_load_dwordx4 v[12:15], v[6:7], off offset:-2048
	global_load_dwordx4 v[16:19], v[2:3], off offset:128
	global_load_dwordx4 v[20:23], v[4:5], off offset:128
	ds_read_b128 v[40:43], v140
	ds_read_b128 v[44:47], v140 offset:1024
	ds_read_b128 v[48:51], v144 offset:16384
	ds_read_b128 v[52:55], v144 offset:17408
	ds_read_b128 v[56:59], v140 offset:2048
	ds_read_b128 v[60:63], v140 offset:3072
	ds_read_b128 v[68:71], v144 offset:18432
	ds_read_b128 v[72:75], v144 offset:19456
	s_setprio 1
	s_waitcnt lgkmcnt(5)
	v_mfma_f32_16x16x32_bf16 v[76:79], v[48:51], v[40:43], 0
	s_waitcnt lgkmcnt(4)
	v_mfma_f32_16x16x32_bf16 v[80:83], v[52:55], v[40:43], 0
	s_waitcnt lgkmcnt(1)
	v_mfma_f32_16x16x32_bf16 v[84:87], v[68:71], v[40:43], 0
	s_waitcnt lgkmcnt(0)
	v_mfma_f32_16x16x32_bf16 v[40:43], v[72:75], v[40:43], 0
	v_mfma_f32_16x16x32_bf16 v[88:91], v[48:51], v[44:47], 0
	v_mfma_f32_16x16x32_bf16 v[92:95], v[52:55], v[44:47], 0
	v_mfma_f32_16x16x32_bf16 v[96:99], v[68:71], v[44:47], 0
	v_mfma_f32_16x16x32_bf16 v[44:47], v[72:75], v[44:47], 0
	v_mfma_f32_16x16x32_bf16 v[100:103], v[48:51], v[56:59], 0
	v_mfma_f32_16x16x32_bf16 v[104:107], v[52:55], v[56:59], 0
	v_mfma_f32_16x16x32_bf16 v[108:111], v[68:71], v[56:59], 0
	v_mfma_f32_16x16x32_bf16 v[56:59], v[72:75], v[56:59], 0
	v_mfma_f32_16x16x32_bf16 v[48:51], v[48:51], v[60:63], 0
	v_mfma_f32_16x16x32_bf16 v[52:55], v[52:55], v[60:63], 0
	v_mfma_f32_16x16x32_bf16 v[68:71], v[68:71], v[60:63], 0
	v_mfma_f32_16x16x32_bf16 v[60:63], v[72:75], v[60:63], 0
	s_setprio 0
	s_waitcnt vmcnt(5)
	ds_write_b128 v148, v[32:35] offset:8192
	s_waitcnt vmcnt(4)
	ds_write_b128 v148, v[36:39] offset:12288
	ds_write_b128 v148, v[24:27] offset:24576
	ds_write_b128 v148, v[28:31] offset:28672
	s_waitcnt lgkmcnt(0)
	s_barrier
	global_load_dwordx4 v[24:27], v[0:1], off offset:-1024
	global_load_dwordx4 v[28:31], v[6:7], off offset:-1024
	global_load_dwordx4 v[32:35], v[2:3], off offset:192
	global_load_dwordx4 v[36:39], v[4:5], off offset:192
	ds_read_b128 v[72:75], v140 offset:8192
	ds_read_b128 v[112:115], v144 offset:24576
	ds_read_b128 v[116:119], v140 offset:9216
	ds_read_b128 v[120:123], v144 offset:25600
	ds_read_b128 v[124:127], v140 offset:10240
	ds_read_b128 v[128:131], v144 offset:26624
	ds_read_b128 v[132:135], v140 offset:11264
	ds_read_b128 v[136:139], v144 offset:27648
	s_setprio 1
	s_waitcnt lgkmcnt(6)
	v_mfma_f32_16x16x32_bf16 v[76:79], v[112:115], v[72:75], v[76:79]
	s_waitcnt lgkmcnt(4)
	v_mfma_f32_16x16x32_bf16 v[80:83], v[120:123], v[72:75], v[80:83]
	s_waitcnt lgkmcnt(2)
	v_mfma_f32_16x16x32_bf16 v[84:87], v[128:131], v[72:75], v[84:87]
	s_waitcnt lgkmcnt(0)
	v_mfma_f32_16x16x32_bf16 v[40:43], v[136:139], v[72:75], v[40:43]
	v_mfma_f32_16x16x32_bf16 v[72:75], v[112:115], v[116:119], v[88:91]
	v_mfma_f32_16x16x32_bf16 v[88:91], v[120:123], v[116:119], v[92:95]
	v_mfma_f32_16x16x32_bf16 v[92:95], v[128:131], v[116:119], v[96:99]
	v_mfma_f32_16x16x32_bf16 v[44:47], v[136:139], v[116:119], v[44:47]
	v_mfma_f32_16x16x32_bf16 v[96:99], v[112:115], v[124:127], v[100:103]
	v_mfma_f32_16x16x32_bf16 v[100:103], v[120:123], v[124:127], v[104:107]
	v_mfma_f32_16x16x32_bf16 v[104:107], v[128:131], v[124:127], v[108:111]
	v_mfma_f32_16x16x32_bf16 v[56:59], v[136:139], v[124:127], v[56:59]
	v_mfma_f32_16x16x32_bf16 v[48:51], v[112:115], v[132:135], v[48:51]
	v_mfma_f32_16x16x32_bf16 v[52:55], v[120:123], v[132:135], v[52:55]
	v_mfma_f32_16x16x32_bf16 v[68:71], v[128:131], v[132:135], v[68:71]
	v_mfma_f32_16x16x32_bf16 v[60:63], v[136:139], v[132:135], v[60:63]
	s_setprio 0
	s_waitcnt vmcnt(7)
	ds_write_b128 v148, v[8:11]
	s_waitcnt vmcnt(6)
	ds_write_b128 v149, v[12:15]
	s_waitcnt vmcnt(5)
	ds_write_b128 v148, v[16:19] offset:16384
	s_waitcnt vmcnt(4)
	ds_write_b128 v149, v[20:23] offset:16384
	s_waitcnt lgkmcnt(0)
	s_barrier
	global_load_dwordx4 v[8:11], v[0:1], off
	global_load_dwordx4 v[12:15], v[6:7], off
	global_load_dwordx4 v[16:19], v[2:3], off offset:256
	global_load_dwordx4 v[20:23], v[4:5], off offset:256
	ds_read_b128 v[108:111], v140
	ds_read_b128 v[112:115], v144 offset:16384
	ds_read_b128 v[116:119], v140 offset:1024
	ds_read_b128 v[120:123], v144 offset:17408
	ds_read_b128 v[124:127], v140 offset:2048
	ds_read_b128 v[128:131], v144 offset:18432
	ds_read_b128 v[132:135], v140 offset:3072
	ds_read_b128 v[136:139], v144 offset:19456
	s_setprio 1
	s_waitcnt lgkmcnt(6)
	v_mfma_f32_16x16x32_bf16 v[76:79], v[112:115], v[108:111], v[76:79]
	s_waitcnt lgkmcnt(4)
	v_mfma_f32_16x16x32_bf16 v[80:83], v[120:123], v[108:111], v[80:83]
	s_waitcnt lgkmcnt(2)
	v_mfma_f32_16x16x32_bf16 v[84:87], v[128:131], v[108:111], v[84:87]
	s_waitcnt lgkmcnt(0)
	v_mfma_f32_16x16x32_bf16 v[40:43], v[136:139], v[108:111], v[40:43]
	v_mfma_f32_16x16x32_bf16 v[72:75], v[112:115], v[116:119], v[72:75]
	v_mfma_f32_16x16x32_bf16 v[88:91], v[120:123], v[116:119], v[88:91]
	v_mfma_f32_16x16x32_bf16 v[92:95], v[128:131], v[116:119], v[92:95]
	v_mfma_f32_16x16x32_bf16 v[44:47], v[136:139], v[116:119], v[44:47]
	v_mfma_f32_16x16x32_bf16 v[96:99], v[112:115], v[124:127], v[96:99]
	v_mfma_f32_16x16x32_bf16 v[100:103], v[120:123], v[124:127], v[100:103]
	v_mfma_f32_16x16x32_bf16 v[104:107], v[128:131], v[124:127], v[104:107]
	v_mfma_f32_16x16x32_bf16 v[56:59], v[136:139], v[124:127], v[56:59]
	v_mfma_f32_16x16x32_bf16 v[48:51], v[112:115], v[132:135], v[48:51]
	v_mfma_f32_16x16x32_bf16 v[52:55], v[120:123], v[132:135], v[52:55]
	v_mfma_f32_16x16x32_bf16 v[68:71], v[128:131], v[132:135], v[68:71]
	v_mfma_f32_16x16x32_bf16 v[60:63], v[136:139], v[132:135], v[60:63]
	s_setprio 0
	s_waitcnt vmcnt(7)
	ds_write_b128 v148, v[24:27] offset:8192
	s_waitcnt vmcnt(6)
	ds_write_b128 v148, v[28:31] offset:12288
	s_waitcnt vmcnt(5)
	ds_write_b128 v148, v[32:35] offset:24576
	s_waitcnt vmcnt(4)
	ds_write_b128 v148, v[36:39] offset:28672
	s_waitcnt lgkmcnt(0)
	s_barrier
	global_load_dwordx4 v[24:27], v[0:1], off offset:1024
	global_load_dwordx4 v[28:31], v[6:7], off offset:1024
	global_load_dwordx4 v[32:35], v[2:3], off offset:320
	global_load_dwordx4 v[36:39], v[4:5], off offset:320
	ds_read_b128 v[108:111], v140 offset:8192
	ds_read_b128 v[112:115], v144 offset:24576
	ds_read_b128 v[116:119], v140 offset:9216
	ds_read_b128 v[120:123], v144 offset:25600
	ds_read_b128 v[124:127], v140 offset:10240
	ds_read_b128 v[128:131], v144 offset:26624
	ds_read_b128 v[132:135], v140 offset:11264
	ds_read_b128 v[136:139], v144 offset:27648
	s_setprio 1
	s_waitcnt lgkmcnt(6)
	v_mfma_f32_16x16x32_bf16 v[76:79], v[112:115], v[108:111], v[76:79]
	s_waitcnt lgkmcnt(4)
	v_mfma_f32_16x16x32_bf16 v[80:83], v[120:123], v[108:111], v[80:83]
	s_waitcnt lgkmcnt(2)
	v_mfma_f32_16x16x32_bf16 v[84:87], v[128:131], v[108:111], v[84:87]
	s_waitcnt lgkmcnt(0)
	v_mfma_f32_16x16x32_bf16 v[40:43], v[136:139], v[108:111], v[40:43]
	v_mfma_f32_16x16x32_bf16 v[72:75], v[112:115], v[116:119], v[72:75]
	v_mfma_f32_16x16x32_bf16 v[88:91], v[120:123], v[116:119], v[88:91]
	v_mfma_f32_16x16x32_bf16 v[92:95], v[128:131], v[116:119], v[92:95]
	v_mfma_f32_16x16x32_bf16 v[44:47], v[136:139], v[116:119], v[44:47]
	v_mfma_f32_16x16x32_bf16 v[96:99], v[112:115], v[124:127], v[96:99]
	v_mfma_f32_16x16x32_bf16 v[100:103], v[120:123], v[124:127], v[100:103]
	v_mfma_f32_16x16x32_bf16 v[104:107], v[128:131], v[124:127], v[104:107]
	v_mfma_f32_16x16x32_bf16 v[56:59], v[136:139], v[124:127], v[56:59]
	v_mfma_f32_16x16x32_bf16 v[48:51], v[112:115], v[132:135], v[48:51]
	v_mfma_f32_16x16x32_bf16 v[52:55], v[120:123], v[132:135], v[52:55]
	v_mfma_f32_16x16x32_bf16 v[68:71], v[128:131], v[132:135], v[68:71]
	v_mfma_f32_16x16x32_bf16 v[60:63], v[136:139], v[132:135], v[60:63]
	s_setprio 0
	s_waitcnt vmcnt(7)
	ds_write_b128 v148, v[8:11]
	s_waitcnt vmcnt(6)
	ds_write_b128 v149, v[12:15]
	s_waitcnt vmcnt(5)
	ds_write_b128 v148, v[16:19] offset:16384
	s_waitcnt vmcnt(4)
	ds_write_b128 v149, v[20:23] offset:16384
	s_waitcnt lgkmcnt(0)
	s_barrier
	global_load_dwordx4 v[8:11], v[0:1], off offset:2048
	global_load_dwordx4 v[12:15], v[6:7], off offset:2048
	global_load_dwordx4 v[16:19], v[2:3], off offset:384
	global_load_dwordx4 v[20:23], v[4:5], off offset:384
	ds_read_b128 v[108:111], v140
	ds_read_b128 v[112:115], v144 offset:16384
	ds_read_b128 v[116:119], v140 offset:1024
	ds_read_b128 v[120:123], v144 offset:17408
	ds_read_b128 v[124:127], v140 offset:2048
	ds_read_b128 v[128:131], v144 offset:18432
	ds_read_b128 v[132:135], v140 offset:3072
	ds_read_b128 v[136:139], v144 offset:19456
	s_setprio 1
	s_waitcnt lgkmcnt(6)
	v_mfma_f32_16x16x32_bf16 v[76:79], v[112:115], v[108:111], v[76:79]
	s_waitcnt lgkmcnt(4)
	v_mfma_f32_16x16x32_bf16 v[80:83], v[120:123], v[108:111], v[80:83]
	s_waitcnt lgkmcnt(2)
	v_mfma_f32_16x16x32_bf16 v[84:87], v[128:131], v[108:111], v[84:87]
	s_waitcnt lgkmcnt(0)
	v_mfma_f32_16x16x32_bf16 v[40:43], v[136:139], v[108:111], v[40:43]
	v_mfma_f32_16x16x32_bf16 v[72:75], v[112:115], v[116:119], v[72:75]
	v_mfma_f32_16x16x32_bf16 v[88:91], v[120:123], v[116:119], v[88:91]
	v_mfma_f32_16x16x32_bf16 v[92:95], v[128:131], v[116:119], v[92:95]
	v_mfma_f32_16x16x32_bf16 v[44:47], v[136:139], v[116:119], v[44:47]
	v_mfma_f32_16x16x32_bf16 v[96:99], v[112:115], v[124:127], v[96:99]
	v_mfma_f32_16x16x32_bf16 v[100:103], v[120:123], v[124:127], v[100:103]
	v_mfma_f32_16x16x32_bf16 v[104:107], v[128:131], v[124:127], v[104:107]
	v_mfma_f32_16x16x32_bf16 v[56:59], v[136:139], v[124:127], v[56:59]
	v_mfma_f32_16x16x32_bf16 v[48:51], v[112:115], v[132:135], v[48:51]
	v_mfma_f32_16x16x32_bf16 v[52:55], v[120:123], v[132:135], v[52:55]
	v_mfma_f32_16x16x32_bf16 v[68:71], v[128:131], v[132:135], v[68:71]
	v_mfma_f32_16x16x32_bf16 v[60:63], v[136:139], v[132:135], v[60:63]
	s_setprio 0
	s_waitcnt vmcnt(7)
	ds_write_b128 v148, v[24:27] offset:8192
	s_waitcnt vmcnt(6)
	ds_write_b128 v148, v[28:31] offset:12288
	s_waitcnt vmcnt(5)
	ds_write_b128 v148, v[32:35] offset:24576
	s_waitcnt vmcnt(4)
	ds_write_b128 v148, v[36:39] offset:28672
	s_waitcnt lgkmcnt(0)
	s_barrier
	global_load_dwordx4 v[24:27], v[0:1], off offset:3072
	global_load_dwordx4 v[28:31], v[6:7], off offset:3072
	global_load_dwordx4 v[32:35], v[2:3], off offset:448
	global_load_dwordx4 v[36:39], v[4:5], off offset:448
	ds_read_b128 v[108:111], v140 offset:8192
	ds_read_b128 v[112:115], v144 offset:24576
	ds_read_b128 v[116:119], v140 offset:9216
	ds_read_b128 v[120:123], v144 offset:25600
	ds_read_b128 v[124:127], v140 offset:10240
	ds_read_b128 v[128:131], v144 offset:26624
	ds_read_b128 v[132:135], v140 offset:11264
	ds_read_b128 v[136:139], v144 offset:27648
	s_setprio 1
	s_waitcnt lgkmcnt(6)
	v_mfma_f32_16x16x32_bf16 v[76:79], v[112:115], v[108:111], v[76:79]
	s_waitcnt lgkmcnt(4)
	v_mfma_f32_16x16x32_bf16 v[80:83], v[120:123], v[108:111], v[80:83]
	s_waitcnt lgkmcnt(2)
	v_mfma_f32_16x16x32_bf16 v[84:87], v[128:131], v[108:111], v[84:87]
	s_waitcnt lgkmcnt(0)
	v_mfma_f32_16x16x32_bf16 v[40:43], v[136:139], v[108:111], v[40:43]
	v_mfma_f32_16x16x32_bf16 v[72:75], v[112:115], v[116:119], v[72:75]
	v_mfma_f32_16x16x32_bf16 v[88:91], v[120:123], v[116:119], v[88:91]
	v_mfma_f32_16x16x32_bf16 v[92:95], v[128:131], v[116:119], v[92:95]
	v_mfma_f32_16x16x32_bf16 v[44:47], v[136:139], v[116:119], v[44:47]
	v_mfma_f32_16x16x32_bf16 v[96:99], v[112:115], v[124:127], v[96:99]
	v_mfma_f32_16x16x32_bf16 v[100:103], v[120:123], v[124:127], v[100:103]
	v_mfma_f32_16x16x32_bf16 v[104:107], v[128:131], v[124:127], v[104:107]
	v_mfma_f32_16x16x32_bf16 v[56:59], v[136:139], v[124:127], v[56:59]
	v_mfma_f32_16x16x32_bf16 v[48:51], v[112:115], v[132:135], v[48:51]
	v_mfma_f32_16x16x32_bf16 v[52:55], v[120:123], v[132:135], v[52:55]
	v_mfma_f32_16x16x32_bf16 v[68:71], v[128:131], v[132:135], v[68:71]
	v_mfma_f32_16x16x32_bf16 v[60:63], v[136:139], v[132:135], v[60:63]
	s_setprio 0
	s_waitcnt vmcnt(7)
	ds_write_b128 v148, v[8:11]
	s_waitcnt vmcnt(6)
	ds_write_b128 v149, v[12:15]
	s_waitcnt vmcnt(5)
	ds_write_b128 v148, v[16:19] offset:16384
	s_waitcnt vmcnt(4)
	ds_write_b128 v149, v[20:23] offset:16384
	s_waitcnt lgkmcnt(0)
	s_barrier
	global_load_dwordx4 v[108:111], v[0:1], off offset:3072
	global_load_dwordx4 v[112:115], v[6:7], off offset:3072
	global_load_dwordx4 v[116:119], v[2:3], off offset:448
	global_load_dwordx4 v[120:123], v[4:5], off offset:448
	ds_read_b128 v[0:3], v140
	ds_read_b128 v[4:7], v144 offset:16384
	ds_read_b128 v[8:11], v140 offset:1024
	ds_read_b128 v[12:15], v144 offset:17408
	ds_read_b128 v[16:19], v140 offset:2048
	ds_read_b128 v[20:23], v144 offset:18432
	ds_read_b128 v[124:127], v140 offset:3072
	ds_read_b128 v[128:131], v144 offset:19456
	s_setprio 1
	s_waitcnt lgkmcnt(6)
	v_mfma_f32_16x16x32_bf16 v[76:79], v[4:7], v[0:3], v[76:79]
	s_waitcnt lgkmcnt(4)
	v_mfma_f32_16x16x32_bf16 v[80:83], v[12:15], v[0:3], v[80:83]
	s_waitcnt lgkmcnt(2)
	v_mfma_f32_16x16x32_bf16 v[84:87], v[20:23], v[0:3], v[84:87]
	s_waitcnt lgkmcnt(0)
	v_mfma_f32_16x16x32_bf16 v[0:3], v[128:131], v[0:3], v[40:43]
	v_mfma_f32_16x16x32_bf16 v[40:43], v[4:7], v[8:11], v[72:75]
	v_mfma_f32_16x16x32_bf16 v[72:75], v[12:15], v[8:11], v[88:91]
	v_mfma_f32_16x16x32_bf16 v[88:91], v[20:23], v[8:11], v[92:95]
	v_mfma_f32_16x16x32_bf16 v[8:11], v[128:131], v[8:11], v[44:47]
	v_mfma_f32_16x16x32_bf16 v[92:95], v[4:7], v[16:19], v[96:99]
	v_mfma_f32_16x16x32_bf16 v[96:99], v[12:15], v[16:19], v[100:103]
	v_mfma_f32_16x16x32_bf16 v[100:103], v[20:23], v[16:19], v[104:107]
	v_mfma_f32_16x16x32_bf16 v[16:19], v[128:131], v[16:19], v[56:59]
	v_mfma_f32_16x16x32_bf16 v[4:7], v[4:7], v[124:127], v[48:51]
	v_mfma_f32_16x16x32_bf16 v[104:107], v[12:15], v[124:127], v[52:55]
	v_mfma_f32_16x16x32_bf16 v[68:71], v[20:23], v[124:127], v[68:71]
	v_mfma_f32_16x16x32_bf16 v[60:63], v[128:131], v[124:127], v[60:63]
	s_setprio 0
	s_waitcnt vmcnt(7)
	ds_write_b128 v148, v[24:27] offset:8192
	s_waitcnt vmcnt(6)
	ds_write_b128 v148, v[28:31] offset:12288
	s_waitcnt vmcnt(5)
	ds_write_b128 v148, v[32:35] offset:24576
	s_waitcnt vmcnt(4)
	ds_write_b128 v148, v[36:39] offset:28672
	s_waitcnt lgkmcnt(0)
	s_barrier
	ds_read_b128 v[12:15], v140 offset:8192
	ds_read_b128 v[124:127], v144 offset:24576
	ds_read_b128 v[20:23], v140 offset:9216
	ds_read_b128 v[128:131], v144 offset:25600
	ds_read_b128 v[132:135], v140 offset:10240
	ds_read_b128 v[136:139], v144 offset:26624
	ds_read_b128 v[140:143], v140 offset:11264
	ds_read_b128 v[144:147], v144 offset:27648
	s_setprio 1
	s_waitcnt lgkmcnt(6)
	v_mfma_f32_16x16x32_bf16 v[76:79], v[124:127], v[12:15], v[76:79]
	s_waitcnt lgkmcnt(4)
	v_mfma_f32_16x16x32_bf16 v[56:59], v[128:131], v[12:15], v[80:83]
	s_waitcnt lgkmcnt(2)
	v_mfma_f32_16x16x32_bf16 v[52:55], v[136:139], v[12:15], v[84:87]
	s_waitcnt lgkmcnt(0)
	v_mfma_f32_16x16x32_bf16 v[48:51], v[144:147], v[12:15], v[0:3]
	v_mfma_f32_16x16x32_bf16 v[44:47], v[124:127], v[20:23], v[40:43]
	v_mfma_f32_16x16x32_bf16 v[40:43], v[128:131], v[20:23], v[72:75]
	v_mfma_f32_16x16x32_bf16 v[36:39], v[136:139], v[20:23], v[88:91]
	v_mfma_f32_16x16x32_bf16 v[32:35], v[144:147], v[20:23], v[8:11]
	v_mfma_f32_16x16x32_bf16 v[28:31], v[124:127], v[132:135], v[92:95]
	v_mfma_f32_16x16x32_bf16 v[24:27], v[128:131], v[132:135], v[96:99]
	v_mfma_f32_16x16x32_bf16 v[20:23], v[136:139], v[132:135], v[100:103]
	v_mfma_f32_16x16x32_bf16 v[16:19], v[144:147], v[132:135], v[16:19]
	v_mfma_f32_16x16x32_bf16 v[12:15], v[124:127], v[140:143], v[4:7]
	v_mfma_f32_16x16x32_bf16 v[8:11], v[128:131], v[140:143], v[104:107]
	v_mfma_f32_16x16x32_bf16 v[4:7], v[136:139], v[140:143], v[68:71]
	v_mfma_f32_16x16x32_bf16 v[0:3], v[144:147], v[140:143], v[60:63]
	s_setprio 0
	s_nop 1
	v_mov_b32_e32 v60, v220
	s_waitcnt vmcnt(3)
	ds_write_b128 v148, v[108:111]
	s_waitcnt vmcnt(2)
	ds_write_b128 v149, v[112:115]
	s_waitcnt vmcnt(1)
	ds_write_b128 v148, v[116:119] offset:16384
	s_waitcnt vmcnt(0)
	ds_write_b128 v149, v[120:123] offset:16384
	s_waitcnt lgkmcnt(0)
	s_barrier
	s_bfe_u32 s0, s35, 0x20007
	v_and_b32_e32 v62, 15, v60
	v_and_b32_e32 v61, 64, v60
	v_ashrrev_i32_e32 v63, 1, v60
	v_lshrrev_b32_e32 v60, 2, v60
	v_and_or_b32 v71, v60, 12, v61
	v_cvt_f32_ubyte0_e32 v60, s0
	v_sub_f32_e32 v60, 0xc0a00000, v60
	v_cmp_gt_f32_e32 vcc, s27, v60
	s_and_b64 s[0:1], vcc, exec
	s_cselect_b32 s0, 0xffffffc0, 0
	v_cndmask_b32_e32 v61, 0, v64, vcc
	v_add_f32_e32 v60, v60, v61
	v_exp_f32_e32 v60, v60
	v_and_or_b32 v72, v63, s26, v62
	v_lshlrev_b32_e32 v63, 7, v63
	v_lshlrev_b32_e32 v62, 7, v62
	v_ldexp_f32 v68, v60, s0
	v_sub_f32_e32 v69, 1.0, v68
	v_add_f32_e32 v60, -1.0, v69
	v_sub_f32_e32 v61, v60, v69
	v_add_f32_e32 v61, 1.0, v61
	v_sub_f32_e64 v60, -v68, v60
	v_add_f32_e32 v70, v60, v61
	v_frexp_mant_f32_e32 v60, v69
	v_cmp_gt_f32_e32 vcc, s28, v60
	v_cvt_f64_f32_e32 v[60:61], v69
	v_frexp_exp_i32_f64_e32 v60, v[60:61]
	v_subbrev_co_u32_e32 v60, vcc, 0, v60, vcc
	v_sub_u32_e32 v61, 0, v60
	v_ldexp_f32 v69, v69, v61
	v_ldexp_f32 v61, v70, v61
	v_add_f32_e32 v70, -1.0, v69
	v_add_f32_e32 v73, 1.0, v70
	v_sub_f32_e32 v73, v69, v73
	v_add_f32_e32 v73, v61, v73
	v_add_f32_e32 v74, v70, v73
	v_sub_f32_e32 v70, v74, v70
	v_sub_f32_e32 v70, v73, v70
	v_add_f32_e32 v73, 1.0, v69
	v_add_f32_e32 v75, -1.0, v73
	v_sub_f32_e32 v69, v69, v75
	v_add_f32_e32 v61, v61, v69
	v_add_f32_e32 v69, v73, v61
	v_sub_f32_e32 v73, v69, v73
	v_sub_f32_e32 v61, v61, v73
	v_rcp_f32_e32 v73, v69
	v_cvt_f32_i32_e32 v60, v60
	v_cmp_nlt_f32_e32 vcc, 1.0, v68
	v_cmp_gt_i32_e64 s[0:1], v72, v71
	v_mul_f32_e32 v75, v74, v73
	v_mul_f32_e32 v80, v69, v75
	v_fma_f32 v81, v75, v69, -v80
	v_fmac_f32_e32 v81, v75, v61
	v_add_f32_e32 v82, v80, v81
	v_sub_f32_e32 v83, v74, v82
	v_sub_f32_e32 v74, v74, v83
	v_sub_f32_e32 v80, v82, v80
	v_sub_f32_e32 v74, v74, v82
	v_add_f32_e32 v70, v70, v74
	v_sub_f32_e32 v74, v80, v81
	v_add_f32_e32 v70, v74, v70
	v_add_f32_e32 v74, v83, v70
	v_mul_f32_e32 v80, v73, v74
	v_mul_f32_e32 v81, v69, v80
	v_fma_f32 v69, v80, v69, -v81
	v_fmac_f32_e32 v69, v80, v61
	v_sub_f32_e32 v61, v83, v74
	v_add_f32_e32 v61, v70, v61
	v_add_f32_e32 v70, v81, v69
	v_sub_f32_e32 v82, v74, v70
	v_sub_f32_e32 v74, v74, v82
	v_sub_f32_e32 v81, v70, v81
	v_sub_f32_e32 v70, v74, v70
	v_add_f32_e32 v61, v61, v70
	v_sub_f32_e32 v69, v81, v69
	v_add_f32_e32 v61, v69, v61
	v_add_f32_e32 v69, v75, v80
	v_add_f32_e32 v61, v82, v61
	v_sub_f32_e32 v70, v69, v75
	v_mul_f32_e32 v61, v73, v61
	v_sub_f32_e32 v70, v80, v70
	v_add_f32_e32 v61, v70, v61
	v_mul_f32_e32 v75, 0x3f317218, v60
	v_add_f32_e32 v70, v69, v61
	v_fma_f32 v80, v60, s29, -v75
	v_mul_f32_e32 v73, v70, v70
	v_fmac_f32_e32 v80, 0xb102e308, v60
	v_sub_f32_e32 v60, v70, v69
	v_fmamk_f32 v74, v73, 0x3e9b6dac, v65
	v_sub_f32_e32 v60, v61, v60
	v_add_f32_e32 v61, v75, v80
	v_fmaak_f32 v74, v73, v74, 0x3f2aaada
	v_sub_f32_e32 v69, v61, v75
	v_ldexp_f32 v75, v70, 1
	v_mul_f32_e32 v70, v70, v73
	v_mul_f32_e32 v70, v70, v74
	v_add_f32_e32 v73, v75, v70
	v_sub_f32_e32 v74, v73, v75
	v_ldexp_f32 v60, v60, 1
	v_sub_f32_e32 v70, v70, v74
	v_add_f32_e32 v60, v60, v70
	v_add_f32_e32 v70, v73, v60
	v_sub_f32_e32 v73, v70, v73
	v_sub_f32_e32 v60, v60, v73
	v_add_f32_e32 v73, v61, v70
	v_sub_f32_e32 v74, v73, v61
	v_sub_f32_e32 v75, v73, v74
	v_sub_f32_e32 v69, v80, v69
	v_sub_f32_e32 v61, v61, v75
	v_sub_f32_e32 v70, v70, v74
	v_add_f32_e32 v61, v70, v61
	v_add_f32_e32 v70, v69, v60
	v_sub_f32_e32 v74, v70, v69
	v_sub_f32_e32 v75, v70, v74
	v_sub_f32_e32 v69, v69, v75
	v_sub_f32_e32 v60, v60, v74
	v_add_f32_e32 v61, v70, v61
	v_add_f32_e32 v60, v60, v69
	v_add_f32_e32 v69, v73, v61
	v_sub_f32_e32 v70, v69, v73
	v_sub_f32_e32 v61, v61, v70
	v_add_f32_e32 v60, v60, v61
	v_add_f32_e32 v60, v69, v60
	v_cndmask_b32_e32 v60, v66, v60, vcc
	v_cmp_neq_f32_e32 vcc, 1.0, v68
	v_or_b32_e32 v75, 1, v71
	v_sub_u32_e32 v61, v72, v75
	v_cndmask_b32_e32 v60, v67, v60, vcc
	v_cmp_gt_f32_e32 vcc, s30, v68
	v_or_b32_e32 v73, 2, v71
	v_cvt_f32_i32_e32 v61, v61
	v_cndmask_b32_e64 v68, v60, -v68, vcc
	v_sub_u32_e32 v60, v72, v71
	v_cvt_f32_i32_e32 v60, v60
	v_sub_u32_e32 v70, v72, v73
	v_or_b32_e32 v74, 3, v71
	v_cvt_f32_i32_e32 v70, v70
	v_mul_f32_e32 v60, v68, v60
	v_mul_f32_e32 v60, 0x3fb8aa3b, v60
	v_exp_f32_e32 v69, v60
	v_mul_f32_e32 v61, v68, v61
	v_mul_f32_e32 v61, 0x3fb8aa3b, v61
	v_mul_f32_e32 v70, v68, v70
	v_mul_f32_e32 v60, v76, v69
	v_sub_u32_e32 v76, v72, v74
	v_cvt_f32_i32_e32 v76, v76
	v_exp_f32_e32 v61, v61
	v_mul_f32_e32 v70, 0x3fb8aa3b, v70
	v_exp_f32_e32 v70, v70
	v_mul_f32_e32 v76, v68, v76
	v_mul_f32_e32 v76, 0x3fb8aa3b, v76
	v_exp_f32_e32 v76, v76
	v_mul_f32_e32 v61, v77, v61
	v_cndmask_b32_e64 v61, 0, v61, s[0:1]
	v_mul_f32_e32 v70, v78, v70
	v_cmp_ge_i32_e64 s[0:1], v72, v73
	v_cmp_lt_i32_e32 vcc, v72, v71
	v_mul_f32_e32 v76, v79, v76
	v_cndmask_b32_e64 v70, 0, v70, s[0:1]
	v_cmp_ge_i32_e64 s[0:1], v72, v74
	v_and_b32_e32 v62, s31, v63
	v_cndmask_b32_e64 v60, v60, 0, vcc
	v_cndmask_b32_e64 v76, 0, v76, s[0:1]
	v_ashrrev_i32_e32 v63, 31, v62
	v_cvt_pk_bf16_f32 v60, v60, v61
	v_cvt_pk_bf16_f32 v61, v70, v76
	v_lshlrev_b64 v[62:63], 1, v[62:63]
	v_and_b32_e32 v76, 64, v71
	v_lshlrev_b32_e32 v76, 5, v76
	v_and_b32_e32 v253, 8, v71
	v_lshl_or_b32 v76, v253, 5, v76
	v_and_b32_e32 v253, 4, v71
	v_lshl_or_b32 v76, v253, 1, v76
	v_and_b32_e32 v253, 15, v72
	v_lshl_or_b32 v76, v253, 4, v76
	s_add_u32 s20, s72, s14
	v_or_b32_e32 v62, v62, v76
	s_addc_u32 s21, s73, s15
	v_lshl_add_u64 v[62:63], s[20:21], 0, v[62:63]
	v_add_co_u32_e64 v62, s[0:1], s34, v62
	v_or_b32_e32 v70, 16, v71
	s_nop 0
	v_addc_co_u32_e64 v63, s[0:1], 0, v63, s[0:1]
	global_store_dwordx2 v[62:63], v[60:61], off
	v_sub_u32_e32 v60, v72, v70
	v_cvt_f32_i32_e32 v60, v60
	v_or_b32_e32 v61, 17, v71
	v_cmp_ge_i32_e64 s[0:1], v72, v70
	v_mul_f32_e32 v40, v40, v69
	v_mul_f32_e32 v60, v68, v60
	v_mul_f32_e32 v60, 0x3fb8aa3b, v60
	v_exp_f32_e32 v60, v60
	v_cndmask_b32_e64 v40, v40, 0, vcc
	v_mul_f32_e32 v20, v20, v69
	v_cndmask_b32_e64 v20, v20, 0, vcc
	v_mul_f32_e32 v56, v56, v60
	v_sub_u32_e32 v60, v72, v61
	v_cvt_f32_i32_e32 v60, v60
	v_cndmask_b32_e64 v56, 0, v56, s[0:1]
	v_cmp_ge_i32_e64 s[0:1], v72, v61
	s_add_i32 s35, s35, s74
	v_mul_f32_e32 v60, v68, v60
	v_mul_f32_e32 v60, 0x3fb8aa3b, v60
	v_exp_f32_e32 v60, v60
	s_add_u32 s4, s4, s8
	v_mul_f32_e32 v0, v0, v69
	s_addc_u32 s5, s5, s9
	v_mul_f32_e32 v57, v57, v60
	v_or_b32_e32 v60, 18, v71
	v_sub_u32_e32 v77, v72, v60
	v_cvt_f32_i32_e32 v77, v77
	v_cndmask_b32_e64 v57, 0, v57, s[0:1]
	v_cmp_ge_i32_e64 s[0:1], v72, v60
	v_cvt_pk_bf16_f32 v56, v56, v57
	v_mul_f32_e32 v77, v68, v77
	v_mul_f32_e32 v77, 0x3fb8aa3b, v77
	v_exp_f32_e32 v77, v77
	v_cndmask_b32_e64 v0, v0, 0, vcc
	s_add_u32 s14, s14, s16
	s_addc_u32 s15, s15, s17
	v_mul_f32_e32 v58, v58, v77
	v_cndmask_b32_e64 v77, 0, v58, s[0:1]
	v_or_b32_e32 v58, 19, v71
	v_sub_u32_e32 v78, v72, v58
	v_cvt_f32_i32_e32 v78, v78
	v_cmp_ge_i32_e64 s[0:1], v72, v58
	s_cmpk_lt_i32 s35, 0x400
	v_mul_f32_e32 v78, v68, v78
	v_mul_f32_e32 v78, 0x3fb8aa3b, v78
	v_exp_f32_e32 v78, v78
	s_nop 0
	v_mul_f32_e32 v59, v59, v78
	v_cndmask_b32_e64 v59, 0, v59, s[0:1]
	v_cvt_pk_bf16_f32 v57, v77, v59
	global_store_dwordx2 v[62:63], v[56:57], off offset:512
	v_or_b32_e32 v57, 32, v71
	v_sub_u32_e32 v56, v72, v57
	v_cvt_f32_i32_e32 v56, v56
	v_cmp_ge_i32_e64 s[0:1], v72, v57
	v_mul_f32_e32 v56, v68, v56
	v_mul_f32_e32 v56, 0x3fb8aa3b, v56
	v_exp_f32_e32 v56, v56
	s_nop 0
	v_mul_f32_e32 v52, v52, v56
	v_or_b32_e32 v56, 33, v71
	v_cndmask_b32_e64 v59, 0, v52, s[0:1]
	v_sub_u32_e32 v52, v72, v56
	v_cvt_f32_i32_e32 v52, v52
	v_cmp_ge_i32_e64 s[0:1], v72, v56
	v_mul_f32_e32 v52, v68, v52
	v_mul_f32_e32 v52, 0x3fb8aa3b, v52
	v_exp_f32_e32 v52, v52
	s_nop 0
	v_mul_f32_e32 v52, v53, v52
	v_or_b32_e32 v53, 34, v71
	v_cndmask_b32_e64 v77, 0, v52, s[0:1]
	v_sub_u32_e32 v52, v72, v53
	v_cvt_f32_i32_e32 v52, v52
	v_cmp_ge_i32_e64 s[0:1], v72, v53
	v_mul_f32_e32 v52, v68, v52
	v_mul_f32_e32 v52, 0x3fb8aa3b, v52
	v_exp_f32_e32 v52, v52
	s_nop 0
	v_mul_f32_e32 v52, v54, v52
	v_cndmask_b32_e64 v78, 0, v52, s[0:1]
	v_or_b32_e32 v52, 35, v71
	v_sub_u32_e32 v54, v72, v52
	v_cvt_f32_i32_e32 v54, v54
	v_cmp_ge_i32_e64 s[0:1], v72, v52
	v_mul_f32_e32 v54, v68, v54
	v_mul_f32_e32 v54, 0x3fb8aa3b, v54
	v_exp_f32_e32 v54, v54
	s_nop 0
	v_mul_f32_e32 v54, v55, v54
	v_cndmask_b32_e64 v55, 0, v54, s[0:1]
	v_cvt_pk_bf16_f32 v55, v78, v55
	v_cvt_pk_bf16_f32 v54, v59, v77
	global_store_dwordx2 v[62:63], v[54:55], off offset:1024
	v_or_b32_e32 v55, 48, v71
	v_sub_u32_e32 v54, v72, v55
	v_cvt_f32_i32_e32 v54, v54
	v_cmp_ge_i32_e64 s[0:1], v72, v55
	v_mul_f32_e32 v54, v68, v54
	v_mul_f32_e32 v54, 0x3fb8aa3b, v54
	v_exp_f32_e32 v54, v54
	s_nop 0
	v_mul_f32_e32 v48, v48, v54
	v_or_b32_e32 v54, 49, v71
	v_cndmask_b32_e64 v59, 0, v48, s[0:1]
	v_sub_u32_e32 v48, v72, v54
	v_cvt_f32_i32_e32 v48, v48
	v_cmp_ge_i32_e64 s[0:1], v72, v54
	v_mul_f32_e32 v48, v68, v48
	v_mul_f32_e32 v48, 0x3fb8aa3b, v48
	v_exp_f32_e32 v48, v48
	s_nop 0
	v_mul_f32_e32 v48, v49, v48
	v_or_b32_e32 v49, 50, v71
	v_cndmask_b32_e64 v77, 0, v48, s[0:1]
	v_sub_u32_e32 v48, v72, v49
	v_cvt_f32_i32_e32 v48, v48
	v_cmp_ge_i32_e64 s[0:1], v72, v49
	v_mul_f32_e32 v48, v68, v48
	v_mul_f32_e32 v48, 0x3fb8aa3b, v48
	v_exp_f32_e32 v48, v48
	s_nop 0
	v_mul_f32_e32 v48, v50, v48
	v_cndmask_b32_e64 v78, 0, v48, s[0:1]
	v_or_b32_e32 v48, 51, v71
	v_sub_u32_e32 v50, v72, v48
	v_cvt_f32_i32_e32 v50, v50
	v_cmp_ge_i32_e64 s[0:1], v72, v48
	v_mul_f32_e32 v50, v68, v50
	v_mul_f32_e32 v50, 0x3fb8aa3b, v50
	v_exp_f32_e32 v50, v50
	s_nop 0
	v_mul_f32_e32 v50, v51, v50
	v_cndmask_b32_e64 v51, 0, v50, s[0:1]
	v_cvt_pk_bf16_f32 v50, v59, v77
	v_cvt_pk_bf16_f32 v51, v78, v51
	global_store_dwordx2 v[62:63], v[50:51], off offset:1536
	v_or_b32_e32 v50, 16, v72
	v_sub_u32_e32 v51, v50, v71
	v_cvt_f32_i32_e32 v51, v51
	v_cmp_ge_i32_e64 s[0:1], v50, v71
	v_mul_f32_e32 v51, v68, v51
	v_mul_f32_e32 v51, 0x3fb8aa3b, v51
	v_exp_f32_e32 v51, v51
	s_nop 0
	v_mul_f32_e32 v44, v44, v51
	v_sub_u32_e32 v51, v50, v75
	v_cvt_f32_i32_e32 v51, v51
	v_cndmask_b32_e64 v44, 0, v44, s[0:1]
	v_cmp_gt_i32_e64 s[0:1], v50, v71
	v_mul_f32_e32 v51, v68, v51
	v_mul_f32_e32 v51, 0x3fb8aa3b, v51
	v_exp_f32_e32 v51, v51
	s_nop 0
	v_mul_f32_e32 v45, v45, v51
	v_sub_u32_e32 v51, v50, v73
	v_cvt_f32_i32_e32 v51, v51
	v_cndmask_b32_e64 v45, 0, v45, s[0:1]
	v_cmp_ge_i32_e64 s[0:1], v50, v73
	v_cvt_pk_bf16_f32 v44, v44, v45
	v_mul_f32_e32 v51, v68, v51
	v_mul_f32_e32 v51, 0x3fb8aa3b, v51
	v_exp_f32_e32 v51, v51
	s_nop 0
	v_mul_f32_e32 v46, v46, v51
	v_sub_u32_e32 v51, v50, v74
	v_cvt_f32_i32_e32 v51, v51
	v_cndmask_b32_e64 v46, 0, v46, s[0:1]
	v_cmp_ge_i32_e64 s[0:1], v50, v74
	v_mul_f32_e32 v51, v68, v51
	v_mul_f32_e32 v51, 0x3fb8aa3b, v51
	v_exp_f32_e32 v51, v51
	s_nop 0
	v_mul_f32_e32 v47, v47, v51
	v_cndmask_b32_e64 v47, 0, v47, s[0:1]
	v_cvt_pk_bf16_f32 v45, v46, v47
	v_lshlrev_b32_e32 v46, 7, v50
	v_and_b32_e32 v46, 0xfffff87f, v46
	v_ashrrev_i32_e32 v47, 31, v46
	v_lshlrev_b64 v[46:47], 1, v[46:47]
	v_or_b32_e32 v46, v46, v76
	v_lshl_add_u64 v[46:47], s[20:21], 0, v[46:47]
	v_add_co_u32_e64 v46, s[0:1], s34, v46
	s_nop 1
	v_addc_co_u32_e64 v47, s[0:1], 0, v47, s[0:1]
	global_store_dwordx2 v[46:47], v[44:45], off
	v_sub_u32_e32 v44, v50, v61
	v_cvt_f32_i32_e32 v44, v44
	v_cmp_ge_i32_e64 s[0:1], v50, v61
	v_mul_f32_e32 v44, v68, v44
	v_mul_f32_e32 v44, 0x3fb8aa3b, v44
	v_exp_f32_e32 v44, v44
	s_nop 0
	v_mul_f32_e32 v41, v41, v44
	v_sub_u32_e32 v44, v50, v60
	v_cvt_f32_i32_e32 v44, v44
	v_cndmask_b32_e64 v41, 0, v41, s[0:1]
	v_cmp_ge_i32_e64 s[0:1], v50, v60
	v_cvt_pk_bf16_f32 v40, v40, v41
	v_mul_f32_e32 v44, v68, v44
	v_mul_f32_e32 v44, 0x3fb8aa3b, v44
	v_exp_f32_e32 v44, v44
	s_nop 0
	v_mul_f32_e32 v42, v42, v44
	v_sub_u32_e32 v44, v50, v58
	v_cvt_f32_i32_e32 v44, v44
	v_cndmask_b32_e64 v42, 0, v42, s[0:1]
	v_cmp_ge_i32_e64 s[0:1], v50, v58
	v_mul_f32_e32 v44, v68, v44
	v_mul_f32_e32 v44, 0x3fb8aa3b, v44
	v_exp_f32_e32 v44, v44
	s_nop 0
	v_mul_f32_e32 v43, v43, v44
	v_cndmask_b32_e64 v43, 0, v43, s[0:1]
	v_cvt_pk_bf16_f32 v41, v42, v43
	global_store_dwordx2 v[46:47], v[40:41], off offset:512
	v_sub_u32_e32 v40, v50, v57
	v_cvt_f32_i32_e32 v40, v40
	v_cmp_ge_i32_e64 s[0:1], v50, v57
	v_mul_f32_e32 v40, v68, v40
	v_mul_f32_e32 v40, 0x3fb8aa3b, v40
	v_exp_f32_e32 v40, v40
	s_nop 0
	v_mul_f32_e32 v36, v36, v40
	v_sub_u32_e32 v40, v50, v56
	v_cvt_f32_i32_e32 v40, v40
	v_cndmask_b32_e64 v36, 0, v36, s[0:1]
	v_cmp_ge_i32_e64 s[0:1], v50, v56
	v_mul_f32_e32 v40, v68, v40
	v_mul_f32_e32 v40, 0x3fb8aa3b, v40
	v_exp_f32_e32 v40, v40
	s_nop 0
	v_mul_f32_e32 v37, v37, v40
	v_sub_u32_e32 v40, v50, v53
	v_cvt_f32_i32_e32 v40, v40
	v_cndmask_b32_e64 v37, 0, v37, s[0:1]
	v_cmp_ge_i32_e64 s[0:1], v50, v53
	v_cvt_pk_bf16_f32 v36, v36, v37
	v_mul_f32_e32 v40, v68, v40
	v_mul_f32_e32 v40, 0x3fb8aa3b, v40
	v_exp_f32_e32 v40, v40
	s_nop 0
	v_mul_f32_e32 v38, v38, v40
	v_sub_u32_e32 v40, v50, v52
	v_cvt_f32_i32_e32 v40, v40
	v_cndmask_b32_e64 v38, 0, v38, s[0:1]
	v_cmp_ge_i32_e64 s[0:1], v50, v52
	v_mul_f32_e32 v40, v68, v40
	v_mul_f32_e32 v40, 0x3fb8aa3b, v40
	v_exp_f32_e32 v40, v40
	s_nop 0
	v_mul_f32_e32 v39, v39, v40
	v_cndmask_b32_e64 v39, 0, v39, s[0:1]
	v_cvt_pk_bf16_f32 v37, v38, v39
	global_store_dwordx2 v[46:47], v[36:37], off offset:1024
	v_sub_u32_e32 v36, v50, v55
	v_cvt_f32_i32_e32 v36, v36
	v_cmp_ge_i32_e64 s[0:1], v50, v55
	v_mul_f32_e32 v36, v68, v36
	v_mul_f32_e32 v36, 0x3fb8aa3b, v36
	v_exp_f32_e32 v36, v36
	s_nop 0
	v_mul_f32_e32 v32, v32, v36
	v_sub_u32_e32 v36, v50, v54
	v_cvt_f32_i32_e32 v36, v36
	v_cndmask_b32_e64 v32, 0, v32, s[0:1]
	v_cmp_ge_i32_e64 s[0:1], v50, v54
	v_mul_f32_e32 v36, v68, v36
	v_mul_f32_e32 v36, 0x3fb8aa3b, v36
	v_exp_f32_e32 v36, v36
	s_nop 0
	v_mul_f32_e32 v33, v33, v36
	v_sub_u32_e32 v36, v50, v49
	v_cvt_f32_i32_e32 v36, v36
	v_cndmask_b32_e64 v33, 0, v33, s[0:1]
	v_cmp_ge_i32_e64 s[0:1], v50, v49
	v_cvt_pk_bf16_f32 v32, v32, v33
	v_mul_f32_e32 v36, v68, v36
	v_mul_f32_e32 v36, 0x3fb8aa3b, v36
	v_exp_f32_e32 v36, v36
	s_nop 0
	v_mul_f32_e32 v34, v34, v36
	v_sub_u32_e32 v36, v50, v48
	v_cvt_f32_i32_e32 v36, v36
	v_cndmask_b32_e64 v34, 0, v34, s[0:1]
	v_cmp_ge_i32_e64 s[0:1], v50, v48
	v_mul_f32_e32 v36, v68, v36
	v_mul_f32_e32 v36, 0x3fb8aa3b, v36
	v_exp_f32_e32 v36, v36
	s_nop 0
	v_mul_f32_e32 v35, v35, v36
	v_cndmask_b32_e64 v35, 0, v35, s[0:1]
	v_cvt_pk_bf16_f32 v33, v34, v35
	global_store_dwordx2 v[46:47], v[32:33], off offset:1536
	v_or_b32_e32 v32, 32, v72
	v_sub_u32_e32 v33, v32, v71
	v_cvt_f32_i32_e32 v33, v33
	v_cmp_ge_i32_e64 s[0:1], v32, v71
	v_mul_f32_e32 v33, v68, v33
	v_mul_f32_e32 v33, 0x3fb8aa3b, v33
	v_exp_f32_e32 v33, v33
	s_nop 0
	v_mul_f32_e32 v28, v28, v33
	v_sub_u32_e32 v33, v32, v75
	v_cvt_f32_i32_e32 v33, v33
	v_cndmask_b32_e64 v28, 0, v28, s[0:1]
	v_cmp_gt_i32_e64 s[0:1], v32, v71
	v_mul_f32_e32 v33, v68, v33
	v_mul_f32_e32 v33, 0x3fb8aa3b, v33
	v_exp_f32_e32 v33, v33
	s_nop 0
	v_mul_f32_e32 v29, v29, v33
	v_sub_u32_e32 v33, v32, v73
	v_cvt_f32_i32_e32 v33, v33
	v_cndmask_b32_e64 v29, 0, v29, s[0:1]
	v_cmp_ge_i32_e64 s[0:1], v32, v73
	v_cvt_pk_bf16_f32 v28, v28, v29
	v_mul_f32_e32 v33, v68, v33
	v_mul_f32_e32 v33, 0x3fb8aa3b, v33
	v_exp_f32_e32 v33, v33
	s_nop 0
	v_mul_f32_e32 v30, v30, v33
	v_sub_u32_e32 v33, v32, v74
	v_cvt_f32_i32_e32 v33, v33
	v_cndmask_b32_e64 v30, 0, v30, s[0:1]
	v_cmp_ge_i32_e64 s[0:1], v32, v74
	v_mul_f32_e32 v33, v68, v33
	v_mul_f32_e32 v33, 0x3fb8aa3b, v33
	v_exp_f32_e32 v33, v33
	s_nop 0
	v_mul_f32_e32 v31, v31, v33
	v_cndmask_b32_e64 v31, 0, v31, s[0:1]
	v_cvt_pk_bf16_f32 v29, v30, v31
	v_lshlrev_b32_e32 v30, 7, v32
	v_and_b32_e32 v30, 0xfffff87f, v30
	v_ashrrev_i32_e32 v31, 31, v30
	v_lshlrev_b64 v[30:31], 1, v[30:31]
	v_or_b32_e32 v30, v30, v76
	v_lshl_add_u64 v[30:31], s[20:21], 0, v[30:31]
	v_add_co_u32_e64 v30, s[0:1], s34, v30
	s_nop 1
	v_addc_co_u32_e64 v31, s[0:1], 0, v31, s[0:1]
	global_store_dwordx2 v[30:31], v[28:29], off
	v_sub_u32_e32 v28, v32, v70
	v_cvt_f32_i32_e32 v28, v28
	v_cmp_ge_i32_e64 s[0:1], v32, v70
	v_mul_f32_e32 v28, v68, v28
	v_mul_f32_e32 v28, 0x3fb8aa3b, v28
	v_exp_f32_e32 v28, v28
	s_nop 0
	v_mul_f32_e32 v24, v24, v28
	v_sub_u32_e32 v28, v32, v61
	v_cvt_f32_i32_e32 v28, v28
	v_cndmask_b32_e64 v24, 0, v24, s[0:1]
	v_cmp_ge_i32_e64 s[0:1], v32, v61
	v_mul_f32_e32 v28, v68, v28
	v_mul_f32_e32 v28, 0x3fb8aa3b, v28
	v_exp_f32_e32 v28, v28
	s_nop 0
	v_mul_f32_e32 v25, v25, v28
	v_sub_u32_e32 v28, v32, v60
	v_cvt_f32_i32_e32 v28, v28
	v_cndmask_b32_e64 v25, 0, v25, s[0:1]
	v_cmp_ge_i32_e64 s[0:1], v32, v60
	v_cvt_pk_bf16_f32 v24, v24, v25
	v_mul_f32_e32 v28, v68, v28
	v_mul_f32_e32 v28, 0x3fb8aa3b, v28
	v_exp_f32_e32 v28, v28
	s_nop 0
	v_mul_f32_e32 v26, v26, v28
	v_sub_u32_e32 v28, v32, v58
	v_cvt_f32_i32_e32 v28, v28
	v_cndmask_b32_e64 v26, 0, v26, s[0:1]
	v_cmp_ge_i32_e64 s[0:1], v32, v58
	v_mul_f32_e32 v28, v68, v28
	v_mul_f32_e32 v28, 0x3fb8aa3b, v28
	v_exp_f32_e32 v28, v28
	s_nop 0
	v_mul_f32_e32 v27, v27, v28
	v_cndmask_b32_e64 v27, 0, v27, s[0:1]
	v_cvt_pk_bf16_f32 v25, v26, v27
	global_store_dwordx2 v[30:31], v[24:25], off offset:512
	v_sub_u32_e32 v24, v32, v56
	v_cvt_f32_i32_e32 v24, v24
	v_cmp_ge_i32_e64 s[0:1], v32, v56
	v_mul_f32_e32 v24, v68, v24
	v_mul_f32_e32 v24, 0x3fb8aa3b, v24
	v_exp_f32_e32 v24, v24
	s_nop 0
	v_mul_f32_e32 v21, v21, v24
	v_sub_u32_e32 v24, v32, v53
	v_cvt_f32_i32_e32 v24, v24
	v_cndmask_b32_e64 v21, 0, v21, s[0:1]
	v_cmp_ge_i32_e64 s[0:1], v32, v53
	v_cvt_pk_bf16_f32 v20, v20, v21
	v_mul_f32_e32 v24, v68, v24
	v_mul_f32_e32 v24, 0x3fb8aa3b, v24
	v_exp_f32_e32 v24, v24
	s_nop 0
	v_mul_f32_e32 v22, v22, v24
	v_sub_u32_e32 v24, v32, v52
	v_cvt_f32_i32_e32 v24, v24
	v_cndmask_b32_e64 v22, 0, v22, s[0:1]
	v_cmp_ge_i32_e64 s[0:1], v32, v52
	v_mul_f32_e32 v24, v68, v24
	v_mul_f32_e32 v24, 0x3fb8aa3b, v24
	v_exp_f32_e32 v24, v24
	s_nop 0
	v_mul_f32_e32 v23, v23, v24
	v_cndmask_b32_e64 v23, 0, v23, s[0:1]
	v_cvt_pk_bf16_f32 v21, v22, v23
	global_store_dwordx2 v[30:31], v[20:21], off offset:1024
	v_sub_u32_e32 v20, v32, v55
	v_cvt_f32_i32_e32 v20, v20
	v_cmp_ge_i32_e64 s[0:1], v32, v55
	v_mul_f32_e32 v20, v68, v20
	v_mul_f32_e32 v20, 0x3fb8aa3b, v20
	v_exp_f32_e32 v20, v20
	s_nop 0
	v_mul_f32_e32 v16, v16, v20
	v_sub_u32_e32 v20, v32, v54
	v_cvt_f32_i32_e32 v20, v20
	v_cndmask_b32_e64 v16, 0, v16, s[0:1]
	v_cmp_ge_i32_e64 s[0:1], v32, v54
	v_mul_f32_e32 v20, v68, v20
	v_mul_f32_e32 v20, 0x3fb8aa3b, v20
	v_exp_f32_e32 v20, v20
	s_nop 0
	v_mul_f32_e32 v17, v17, v20
	v_sub_u32_e32 v20, v32, v49
	v_cvt_f32_i32_e32 v20, v20
	v_cndmask_b32_e64 v17, 0, v17, s[0:1]
	v_cmp_ge_i32_e64 s[0:1], v32, v49
	v_cvt_pk_bf16_f32 v16, v16, v17
	v_mul_f32_e32 v20, v68, v20
	v_mul_f32_e32 v20, 0x3fb8aa3b, v20
	v_exp_f32_e32 v20, v20
	s_nop 0
	v_mul_f32_e32 v18, v18, v20
	v_sub_u32_e32 v20, v32, v48
	v_cvt_f32_i32_e32 v20, v20
	v_cndmask_b32_e64 v18, 0, v18, s[0:1]
	v_cmp_ge_i32_e64 s[0:1], v32, v48
	v_mul_f32_e32 v20, v68, v20
	v_mul_f32_e32 v20, 0x3fb8aa3b, v20
	v_exp_f32_e32 v20, v20
	s_nop 0
	v_mul_f32_e32 v19, v19, v20
	v_cndmask_b32_e64 v19, 0, v19, s[0:1]
	v_cvt_pk_bf16_f32 v17, v18, v19
	global_store_dwordx2 v[30:31], v[16:17], off offset:1536
	v_or_b32_e32 v16, 48, v72
	v_sub_u32_e32 v17, v16, v71
	v_cvt_f32_i32_e32 v17, v17
	v_cmp_ge_i32_e64 s[0:1], v16, v71
	v_cmp_ge_i32_e32 vcc, v16, v54
	v_mul_f32_e32 v17, v68, v17
	v_mul_f32_e32 v17, 0x3fb8aa3b, v17
	v_exp_f32_e32 v17, v17
	s_nop 0
	v_mul_f32_e32 v12, v12, v17
	v_sub_u32_e32 v17, v16, v75
	v_cvt_f32_i32_e32 v17, v17
	v_cndmask_b32_e64 v12, 0, v12, s[0:1]
	v_cmp_gt_i32_e64 s[0:1], v16, v71
	v_mul_f32_e32 v17, v68, v17
	v_mul_f32_e32 v17, 0x3fb8aa3b, v17
	v_exp_f32_e32 v17, v17
	s_nop 0
	v_mul_f32_e32 v13, v13, v17
	v_sub_u32_e32 v17, v16, v73
	v_cvt_f32_i32_e32 v17, v17
	v_cndmask_b32_e64 v13, 0, v13, s[0:1]
	v_cmp_ge_i32_e64 s[0:1], v16, v73
	v_mul_f32_e32 v17, v68, v17
	v_mul_f32_e32 v17, 0x3fb8aa3b, v17
	v_exp_f32_e32 v17, v17
	s_nop 0
	v_mul_f32_e32 v14, v14, v17
	v_cndmask_b32_e64 v17, 0, v14, s[0:1]
	v_sub_u32_e32 v14, v16, v74
	v_cvt_f32_i32_e32 v14, v14
	v_cmp_ge_i32_e64 s[0:1], v16, v74
	v_mul_f32_e32 v14, v68, v14
	v_mul_f32_e32 v14, 0x3fb8aa3b, v14
	v_exp_f32_e32 v14, v14
	s_nop 0
	v_mul_f32_e32 v14, v15, v14
	v_cndmask_b32_e64 v15, 0, v14, s[0:1]
	v_cvt_pk_bf16_f32 v14, v12, v13
	v_lshlrev_b32_e32 v12, 7, v16
	v_and_b32_e32 v12, 0xfffff87f, v12
	v_ashrrev_i32_e32 v13, 31, v12
	v_lshlrev_b64 v[12:13], 1, v[12:13]
	v_or_b32_e32 v12, v12, v76
	v_lshl_add_u64 v[12:13], s[20:21], 0, v[12:13]
	v_add_co_u32_e64 v12, s[0:1], s34, v12
	v_cvt_pk_bf16_f32 v15, v17, v15
	s_nop 1
	v_addc_co_u32_e64 v13, s[0:1], 0, v13, s[0:1]
	global_store_dwordx2 v[12:13], v[14:15], off
	v_sub_u32_e32 v14, v16, v70
	v_cvt_f32_i32_e32 v14, v14
	v_cmp_ge_i32_e64 s[0:1], v16, v70
	v_mul_f32_e32 v14, v68, v14
	v_mul_f32_e32 v14, 0x3fb8aa3b, v14
	v_exp_f32_e32 v14, v14
	s_nop 0
	v_mul_f32_e32 v8, v8, v14
	v_sub_u32_e32 v14, v16, v61
	v_cvt_f32_i32_e32 v14, v14
	v_cndmask_b32_e64 v8, 0, v8, s[0:1]
	v_cmp_ge_i32_e64 s[0:1], v16, v61
	v_mul_f32_e32 v14, v68, v14
	v_mul_f32_e32 v14, 0x3fb8aa3b, v14
	v_exp_f32_e32 v14, v14
	s_nop 0
	v_mul_f32_e32 v9, v9, v14
	v_sub_u32_e32 v14, v16, v60
	v_cvt_f32_i32_e32 v14, v14
	v_cndmask_b32_e64 v9, 0, v9, s[0:1]
	v_cmp_ge_i32_e64 s[0:1], v16, v60
	v_cvt_pk_bf16_f32 v8, v8, v9
	v_mul_f32_e32 v14, v68, v14
	v_mul_f32_e32 v14, 0x3fb8aa3b, v14
	v_exp_f32_e32 v14, v14
	s_nop 0
	v_mul_f32_e32 v10, v10, v14
	v_sub_u32_e32 v14, v16, v58
	v_cvt_f32_i32_e32 v14, v14
	v_cndmask_b32_e64 v10, 0, v10, s[0:1]
	v_cmp_ge_i32_e64 s[0:1], v16, v58
	v_mul_f32_e32 v14, v68, v14
	v_mul_f32_e32 v14, 0x3fb8aa3b, v14
	v_exp_f32_e32 v14, v14
	s_nop 0
	v_mul_f32_e32 v11, v11, v14
	v_cndmask_b32_e64 v11, 0, v11, s[0:1]
	v_cvt_pk_bf16_f32 v9, v10, v11
	global_store_dwordx2 v[12:13], v[8:9], off offset:512
	v_sub_u32_e32 v8, v16, v57
	v_cvt_f32_i32_e32 v8, v8
	v_cmp_ge_i32_e64 s[0:1], v16, v57
	v_mul_f32_e32 v8, v68, v8
	v_mul_f32_e32 v8, 0x3fb8aa3b, v8
	v_exp_f32_e32 v8, v8
	s_nop 0
	v_mul_f32_e32 v4, v4, v8
	v_sub_u32_e32 v8, v16, v56
	v_cvt_f32_i32_e32 v8, v8
	v_cndmask_b32_e64 v4, 0, v4, s[0:1]
	v_cmp_ge_i32_e64 s[0:1], v16, v56
	v_mul_f32_e32 v8, v68, v8
	v_mul_f32_e32 v8, 0x3fb8aa3b, v8
	v_exp_f32_e32 v8, v8
	s_nop 0
	v_mul_f32_e32 v5, v5, v8
	v_sub_u32_e32 v8, v16, v53
	v_cvt_f32_i32_e32 v8, v8
	v_cndmask_b32_e64 v5, 0, v5, s[0:1]
	v_cmp_ge_i32_e64 s[0:1], v16, v53
	v_cvt_pk_bf16_f32 v4, v4, v5
	v_mul_f32_e32 v8, v68, v8
	v_mul_f32_e32 v8, 0x3fb8aa3b, v8
	v_exp_f32_e32 v8, v8
	s_nop 0
	v_mul_f32_e32 v6, v6, v8
	v_sub_u32_e32 v8, v16, v52
	v_cvt_f32_i32_e32 v8, v8
	v_cndmask_b32_e64 v6, 0, v6, s[0:1]
	v_cmp_ge_i32_e64 s[0:1], v16, v52
	v_mul_f32_e32 v8, v68, v8
	v_mul_f32_e32 v8, 0x3fb8aa3b, v8
	v_exp_f32_e32 v8, v8
	s_nop 0
	v_mul_f32_e32 v7, v7, v8
	v_cndmask_b32_e64 v7, 0, v7, s[0:1]
	v_cvt_pk_bf16_f32 v5, v6, v7
	global_store_dwordx2 v[12:13], v[4:5], off offset:1024
	v_sub_u32_e32 v4, v16, v54
	v_cvt_f32_i32_e32 v4, v4
	v_mul_f32_e32 v4, v68, v4
	v_mul_f32_e32 v4, 0x3fb8aa3b, v4
	v_exp_f32_e32 v4, v4
	s_nop 0
	v_mul_f32_e32 v1, v1, v4
	v_sub_u32_e32 v4, v16, v49
	v_cvt_f32_i32_e32 v4, v4
	v_cndmask_b32_e32 v1, 0, v1, vcc
	v_cmp_ge_i32_e32 vcc, v16, v49
	v_cvt_pk_bf16_f32 v0, v0, v1
	v_mul_f32_e32 v4, v68, v4
	v_mul_f32_e32 v4, 0x3fb8aa3b, v4
	v_exp_f32_e32 v4, v4
	s_nop 0
	v_mul_f32_e32 v2, v2, v4
	v_sub_u32_e32 v4, v16, v48
	v_cvt_f32_i32_e32 v4, v4
	v_cndmask_b32_e32 v2, 0, v2, vcc
	v_cmp_ge_i32_e32 vcc, v16, v48
	v_mul_f32_e32 v4, v68, v4
	v_mul_f32_e32 v4, 0x3fb8aa3b, v4
	v_exp_f32_e32 v4, v4
	s_nop 0
	v_mul_f32_e32 v3, v3, v4
	v_cndmask_b32_e32 v3, 0, v3, vcc
	v_cvt_pk_bf16_f32 v1, v2, v3
	global_store_dwordx2 v[12:13], v[0:1], off offset:1536
	s_cbranch_scc1 .LBB0_330
